# EpiOut residual (xb) loads marked nt: the lines are overwritten right after by the same wave's write-through stores, so they are not kept in L2
# speedup vs baseline: 1.0385x; 1.0025x over previous
.LBB0_505:
	s_lshl_b32 s40, s61, 8
	v_mov_b32_e32 v116, v197
	v_mov_b32_e32 v240, v245
	s_or_b32 s40, s40, s52
	s_nop 0
	v_lshl_add_u32 v208, v240, 3, s40
	s_lshl_b32 s40, s60, 8
	s_add_i32 s40, s40, s51
	v_add_u32_e32 v224, s40, v116
	v_ashrrev_i32_e32 v209, 31, v208
	v_lshlrev_b64 v[226:227], 1, v[208:209]
	v_ashrrev_i32_e32 v225, 31, v224
	v_lshl_add_u64 v[116:117], s[2:3], 0, v[226:227]
	v_lshlrev_b64 v[228:229], 11, v[224:225]
	v_lshl_add_u64 v[118:119], v[116:117], 0, v[228:229]
	global_load_dwordx4 v[248:251], v[118:119], off nt
	global_load_dwordx4 v[188:191], v[118:119], off offset:256 nt
	s_mov_b64 s[40:41], 0x8000
	v_lshl_add_u64 v[222:223], v[228:229], 0, s[40:41]
	s_mov_b64 s[40:41], 0x10000
	v_lshl_add_u64 v[220:221], v[228:229], 0, s[40:41]
	s_mov_b64 s[40:41], 0x18000
	v_lshl_add_u64 v[118:119], v[116:117], 0, v[222:223]
	v_lshl_add_u64 v[218:219], v[228:229], 0, s[40:41]
	s_mov_b64 s[40:41], 0x40000
	global_load_dwordx4 v[184:187], v[118:119], off nt
	global_load_dwordx4 v[180:183], v[118:119], off offset:256 nt
	v_lshl_add_u64 v[118:119], v[116:117], 0, v[220:221]
	v_lshl_add_u64 v[216:217], v[228:229], 0, s[40:41]
	s_mov_b64 s[40:41], 0x48000
	global_load_dwordx4 v[176:179], v[118:119], off nt
	global_load_dwordx4 v[172:175], v[118:119], off offset:256 nt
	v_lshl_add_u64 v[118:119], v[116:117], 0, v[218:219]
	v_lshl_add_u64 v[214:215], v[228:229], 0, s[40:41]
	s_mov_b64 s[40:41], 0x50000
	global_load_dwordx4 v[168:171], v[118:119], off nt
	global_load_dwordx4 v[156:159], v[118:119], off offset:256 nt
	v_lshl_add_u64 v[118:119], v[116:117], 0, v[216:217]
	v_lshl_add_u64 v[212:213], v[228:229], 0, s[40:41]
	s_mov_b64 s[40:41], 0x58000
	global_load_dwordx4 v[152:155], v[118:119], off nt
	global_load_dwordx4 v[148:151], v[118:119], off offset:256 nt
	v_lshl_add_u64 v[118:119], v[116:117], 0, v[214:215]
	v_lshl_add_u64 v[210:211], v[228:229], 0, s[40:41]
	global_load_dwordx4 v[144:147], v[118:119], off nt
	global_load_dwordx4 v[136:139], v[118:119], off offset:256 nt
	v_lshl_add_u64 v[118:119], v[116:117], 0, v[212:213]
	v_lshl_add_u64 v[116:117], v[116:117], 0, v[210:211]
	global_load_dwordx4 v[128:131], v[118:119], off nt
	global_load_dwordx4 v[120:123], v[118:119], off offset:256 nt
	global_load_dwordx4 v[124:127], v[116:117], off nt
	s_nop 0
	global_load_dwordx4 v[116:119], v[116:117], off offset:256 nt
	v_cmp_eq_u32_e32 vcc, 0, v240
	v_lshl_add_u64 v[228:229], s[2:3], 0, v[228:229]
	v_lshl_add_u64 v[226:227], v[228:229], 0, v[226:227]
	v_cmp_lt_i32_e64 s[40:41], v234, v235
	s_waitcnt vmcnt(0)
	v_lshlrev_b32_e32 v240, 16, v248
	v_and_b32_e32 v241, 0xffff0000, v248
	v_lshlrev_b32_e32 v248, 16, v249
	v_and_b32_e32 v249, 0xffff0000, v249
	v_pk_add_f32 v[164:165], v[164:165], v[240:241]
	v_lshlrev_b32_e32 v240, 16, v250
	v_and_b32_e32 v241, 0xffff0000, v250
	v_pk_add_f32 v[166:167], v[166:167], v[248:249]
	v_lshlrev_b32_e32 v248, 16, v251
	v_and_b32_e32 v249, 0xffff0000, v251
	v_pk_add_f32 v[240:241], v[160:161], v[240:241]
	v_cvt_pk_bf16_f32 v160, v164, v165
	v_cvt_pk_bf16_f32 v161, v166, v167
	v_pk_add_f32 v[248:249], v[162:163], v[248:249]
	v_cvt_pk_bf16_f32 v162, v240, v241
	s_nop 0
	v_cvt_pk_bf16_f32 v163, v248, v249
	global_store_dwordx4 v[226:227], v[160:163], off sc1
	s_nop 1
	v_mul_f32_e32 v160, v165, v165
	v_mul_f32_e32 v161, v167, v167
	v_fmac_f32_e32 v160, v164, v164
	v_fmac_f32_e32 v161, v166, v166
	v_add_f32_e32 v160, v160, v161
	v_mul_f32_e32 v161, v241, v241
	v_mul_f32_e32 v162, v249, v249
	v_fmac_f32_e32 v161, v240, v240
	v_fmac_f32_e32 v162, v248, v248
	v_add_f32_e32 v161, v161, v162
	v_add_f32_e32 v164, v160, v161
	v_lshlrev_b32_e32 v160, 16, v188
	v_and_b32_e32 v161, 0xffff0000, v188
	v_lshlrev_b32_e32 v162, 16, v189
	v_and_b32_e32 v163, 0xffff0000, v189
	v_pk_add_f32 v[140:141], v[140:141], v[160:161]
	v_lshlrev_b32_e32 v160, 16, v190
	v_and_b32_e32 v161, 0xffff0000, v190
	v_pk_add_f32 v[142:143], v[142:143], v[162:163]
	v_lshlrev_b32_e32 v162, 16, v191
	v_and_b32_e32 v163, 0xffff0000, v191
	v_pk_add_f32 v[160:161], v[132:133], v[160:161]
	v_cvt_pk_bf16_f32 v132, v140, v141
	v_cvt_pk_bf16_f32 v133, v142, v143
	v_pk_add_f32 v[162:163], v[134:135], v[162:163]
	v_cvt_pk_bf16_f32 v134, v160, v161
	s_nop 0
	v_cvt_pk_bf16_f32 v135, v162, v163
	global_store_dwordx4 v[226:227], v[132:135], off offset:256 sc1
	s_nop 1
	v_mul_f32_e32 v132, v141, v141
	v_mul_f32_e32 v133, v143, v143
	v_fmac_f32_e32 v132, v140, v140
	v_fmac_f32_e32 v133, v142, v142
	v_add_f32_e32 v132, v132, v133
	v_mul_f32_e32 v133, v161, v161
	v_mul_f32_e32 v134, v163, v163
	v_fmac_f32_e32 v133, v160, v160
	v_fmac_f32_e32 v134, v162, v162
	v_add_f32_e32 v133, v133, v134
	v_add_f32_e32 v132, v132, v133
	v_cndmask_b32_e64 v133, v231, v234, s[40:41]
	v_add_f32_e32 v132, v164, v132
	v_lshlrev_b32_e32 v134, 2, v133
	ds_bpermute_b32 v133, v134, v132
	v_cmp_lt_i32_e64 s[40:41], v236, v235
	s_waitcnt lgkmcnt(0)
	v_add_f32_e32 v140, v132, v133
	v_cndmask_b32_e64 v132, v231, v236, s[40:41]
	v_lshlrev_b32_e32 v135, 2, v132
	ds_bpermute_b32 v141, v135, v140
	v_lshl_add_u64 v[132:133], v[224:225], 2, s[20:21]
	s_and_saveexec_b64 s[40:41], vcc
	s_mov_b32 s63, 0x25000
	s_cbranch_execz .LBB0_507
	s_waitcnt lgkmcnt(0)
	v_add_f32_e32 v140, v140, v141
	global_atomic_add_f32 v[132:133], v140, off
